# attention steady loop: the '0 + rowsum' add per step folded into the last row-sum add (one VALU op fewer per step; sums are non-negative so the value is unchanged)
# baseline (speedup 1.0000x reference)
.LBB0_548:
	v_add_u32_e32 v0, s0, v222
	ds_read_b64_tr_b16 v[182:183], v0 offset:24576
	ds_read_b64_tr_b16 v[184:185], v0 offset:25088
	v_add_f32_e32 v2, v82, v83
	v_add_f32_e32 v2, v84, v2
	v_add_f32_e32 v2, v85, v2
	v_add_f32_e32 v2, v86, v2
	v_add_f32_e32 v2, v87, v2
	v_cvt_pk_bf16_f32 v146, v82, v83
	v_cvt_pk_bf16_f32 v147, v84, v85
	s_waitcnt lgkmcnt(9)
	v_mfma_f32_32x32x16_bf16 v[98:113], v[178:181], v[142:145], v[228:243]
	ds_read_b64_tr_b16 v[178:179], v0 offset:28672
	ds_read_b64_tr_b16 v[180:181], v0 offset:29184
	v_add_f32_e32 v2, v88, v2
	v_add_f32_e32 v2, v89, v2
	v_add_f32_e32 v2, v90, v2
	v_add_f32_e32 v2, v91, v2
	v_cvt_pk_bf16_f32 v148, v86, v87
	v_cvt_pk_bf16_f32 v149, v88, v89
	s_waitcnt lgkmcnt(10)
	v_mfma_f32_32x32x16_bf16 v[114:129], v[174:177], v[142:145], v[228:243]
	ds_read_b64_tr_b16 v[174:175], v0 offset:25600
	ds_read_b64_tr_b16 v[176:177], v0 offset:26112
	v_add_f32_e32 v2, v92, v2
	v_add_f32_e32 v2, v93, v2
	v_add_f32_e32 v2, v94, v2
	v_add_f32_e32 v2, v95, v2
	v_cvt_pk_bf16_f32 v10, v90, v91
	v_cvt_pk_bf16_f32 v11, v92, v93
	s_waitcnt lgkmcnt(11)
	v_mfma_f32_32x32x16_bf16 v[98:113], v[170:173], v[138:141], v[98:113]
	ds_read_b64_tr_b16 v[170:171], v0 offset:29696
	ds_read_b64_tr_b16 v[172:173], v0 offset:30208
	v_add_f32_e32 v2, v96, v2
	v_add_f32_e32 v2, v97, v2
	v_add_f32_e32 v2, v66, v2
	v_add_f32_e32 v2, v67, v2
	v_cvt_pk_bf16_f32 v12, v94, v95
	v_cvt_pk_bf16_f32 v13, v96, v97
	s_waitcnt lgkmcnt(12)
	v_mfma_f32_32x32x16_bf16 v[114:129], v[166:169], v[138:141], v[114:129]
	ds_read_b64_tr_b16 v[94:95], v0 offset:26624
	ds_read_b64_tr_b16 v[96:97], v0 offset:27136
	v_add_f32_e32 v2, v68, v2
	v_add_f32_e32 v2, v69, v2
	v_add_f32_e32 v2, v70, v2
	v_add_f32_e32 v2, v71, v2
	v_cvt_pk_bf16_f32 v6, v66, v67
	v_cvt_pk_bf16_f32 v7, v68, v69
	s_waitcnt lgkmcnt(13)
	v_mfma_f32_32x32x16_bf16 v[98:113], v[162:165], v[134:137], v[98:113]
	ds_read_b64_tr_b16 v[90:91], v0 offset:30720
	ds_read_b64_tr_b16 v[92:93], v0 offset:31232
	v_add_f32_e32 v2, v72, v2
	v_add_f32_e32 v2, v73, v2
	v_add_f32_e32 v2, v74, v2
	v_add_f32_e32 v2, v75, v2
	v_cvt_pk_bf16_f32 v8, v70, v71
	v_cvt_pk_bf16_f32 v9, v72, v73
	s_waitcnt lgkmcnt(14)
	v_mfma_f32_32x32x16_bf16 v[114:129], v[158:161], v[134:137], v[114:129]
	ds_read_b64_tr_b16 v[86:87], v0 offset:27648
	ds_read_b64_tr_b16 v[88:89], v0 offset:28160
	v_add_f32_e32 v2, v76, v2
	v_add_f32_e32 v2, v77, v2
	v_add_f32_e32 v2, v78, v2
	v_add_f32_e32 v14, v79, v2
	v_cvt_pk_bf16_f32 v2, v74, v75
	v_cvt_pk_bf16_f32 v3, v76, v77
	s_waitcnt lgkmcnt(14)
	v_mfma_f32_32x32x16_bf16 v[98:113], v[154:157], v[130:133], v[98:113]
	ds_read_b64_tr_b16 v[82:83], v0 offset:31744
	ds_read_b64_tr_b16 v[84:85], v0 offset:32256
	v_add_f32_e32 v0, v80, v14
	v_add_f32_e32 v51, v81, v0
	v_cvt_pk_bf16_f32 v4, v78, v79
	v_cvt_pk_bf16_f32 v5, v80, v81
	v_mfma_f32_32x32x16_bf16 v[114:129], v[150:153], v[130:133], v[114:129]
	s_mov_b32 s2, 0xfff50000
	s_mov_b32 s3, -1
	v_lshl_add_u64 v[14:15], v[188:189], 0, s[2:3]
	s_add_i32 s0, s5, s70
	s_mov_b32 s1, m0
	s_mov_b32 m0, s0
	s_nop 0
	global_load_lds_dwordx4 v[14:15], off
	s_mov_b32 m0, s1
	v_lshl_add_u64 v[14:15], v[186:187], 0, s[2:3]
	s_add_i32 s0, s10, s39
	s_mov_b32 s1, m0
	s_mov_b32 m0, s0
	s_nop 0
	global_load_lds_dwordx4 v[14:15], off
	s_mov_b32 m0, s1
	v_add_f32_e32 v192, v50, v51
	s_waitcnt lgkmcnt(0)
	v_max_f32_e32 v0, v98, v99
	v_max3_f32 v244, v100, v101, v115
	v_max3_f32 v0, v0, v114, v116
	v_max3_f32 v0, v0, v117, v102
	v_max3_f32 v244, v244, v104, v105
	v_max3_f32 v0, v0, v103, v118
	v_max3_f32 v244, v244, v120, v121
	v_max3_f32 v0, v0, v119, v106
	v_max3_f32 v244, v244, v108, v109
	v_max3_f32 v0, v0, v107, v122
	v_max3_f32 v244, v244, v124, v125
	v_max3_f32 v0, v0, v123, v110
	v_max3_f32 v244, v244, v112, v113
	v_max3_f32 v0, v0, v111, v126
	v_max3_f32 v244, v244, v128, v129
	v_max3_f32 v0, v0, v127, v244
	v_mov_b32_e32 v50, v0
	s_nop 1
	v_permlane32_swap_b32_e32 v0, v50
	v_max_f32_e32 v50, v50, v50
	v_max_f32_e32 v0, v0, v0
	v_max_f32_e32 v0, v0, v50
	v_cmp_lt_f32_e32 vcc, s71, v0
	s_cmp_lg_u64 vcc, 0
	s_cselect_b64 s[0:1], -1, 0
	s_cbranch_vccnz .LBB0_556

.LBB0_551:
	s_add_i32 s0, s93, 1
	s_add_i32 s1, s10, 0x2000
	s_cmpk_lg_i32 s10, 0x4000
	s_cselect_b32 s92, s1, 0
	v_add_u32_e32 v14, s5, v222
	ds_read_b64_tr_b16 v[154:155], v14 offset:24576
	ds_read_b64_tr_b16 v[156:157], v14 offset:25088
	s_waitcnt lgkmcnt(9)
	v_mfma_f32_32x32x16_bf16 v[82:97], v[102:105], v[142:145], v[228:243]
	v_add_f32_e32 v2, v66, v67
	v_add_f32_e32 v2, v68, v2
	v_add_f32_e32 v2, v69, v2
	v_add_f32_e32 v2, v70, v2
	v_add_f32_e32 v2, v71, v2
	v_cvt_pk_bf16_f32 v146, v66, v67
	v_cvt_pk_bf16_f32 v147, v68, v69
	ds_read_b64_tr_b16 v[150:151], v14 offset:28672
	ds_read_b64_tr_b16 v[152:153], v14 offset:29184
	v_add_f32_e32 v2, v72, v2
	v_add_f32_e32 v2, v73, v2
	v_add_f32_e32 v2, v74, v2
	v_add_f32_e32 v2, v75, v2
	v_cvt_pk_bf16_f32 v148, v70, v71
	v_cvt_pk_bf16_f32 v149, v72, v73
	s_waitcnt lgkmcnt(10)
	v_mfma_f32_32x32x16_bf16 v[98:113], v[98:101], v[142:145], v[228:243]
	ds_read_b64_tr_b16 v[126:127], v14 offset:25600
	ds_read_b64_tr_b16 v[128:129], v14 offset:26112
	s_waitcnt lgkmcnt(11)
	v_mfma_f32_32x32x16_bf16 v[82:97], v[122:125], v[138:141], v[82:97]
	v_add_f32_e32 v2, v76, v2
	v_add_f32_e32 v2, v77, v2
	v_add_f32_e32 v2, v78, v2
	v_add_f32_e32 v2, v79, v2
	v_cvt_pk_bf16_f32 v10, v74, v75
	v_cvt_pk_bf16_f32 v11, v76, v77
	ds_read_b64_tr_b16 v[66:67], v14 offset:29696
	ds_read_b64_tr_b16 v[68:69], v14 offset:30208
	v_add_f32_e32 v2, v80, v2
	v_add_f32_e32 v2, v81, v2
	v_add_f32_e32 v2, v50, v2
	v_add_f32_e32 v2, v51, v2
	v_cvt_pk_bf16_f32 v12, v78, v79
	v_cvt_pk_bf16_f32 v13, v80, v81
	s_waitcnt lgkmcnt(12)
	v_mfma_f32_32x32x16_bf16 v[98:113], v[118:121], v[138:141], v[98:113]
	ds_read_b64_tr_b16 v[122:123], v14 offset:26624
	ds_read_b64_tr_b16 v[124:125], v14 offset:27136
	s_waitcnt lgkmcnt(13)
	v_mfma_f32_32x32x16_bf16 v[82:97], v[166:169], v[134:137], v[82:97]
	v_add_f32_e32 v2, v52, v2
	v_add_f32_e32 v2, v53, v2
	v_add_f32_e32 v2, v54, v2
	v_add_f32_e32 v2, v55, v2
	v_cvt_pk_bf16_f32 v6, v50, v51
	v_cvt_pk_bf16_f32 v7, v52, v53
	ds_read_b64_tr_b16 v[118:119], v14 offset:30720
	ds_read_b64_tr_b16 v[120:121], v14 offset:31232
	v_add_f32_e32 v2, v56, v2
	v_add_f32_e32 v2, v57, v2
	v_add_f32_e32 v2, v58, v2
	v_add_f32_e32 v2, v59, v2
	v_cvt_pk_bf16_f32 v8, v54, v55
	v_cvt_pk_bf16_f32 v9, v56, v57
	s_waitcnt lgkmcnt(14)
	v_mfma_f32_32x32x16_bf16 v[98:113], v[114:117], v[134:137], v[98:113]
	ds_read_b64_tr_b16 v[114:115], v14 offset:27648
	ds_read_b64_tr_b16 v[116:117], v14 offset:28160
	s_waitcnt lgkmcnt(14)
	v_mfma_f32_32x32x16_bf16 v[82:97], v[162:165], v[130:133], v[82:97]
	v_add_f32_e32 v2, v60, v2
	v_add_f32_e32 v2, v61, v2
	v_add_f32_e32 v2, v62, v2
	v_add_f32_e32 v15, v63, v2
	v_cvt_pk_bf16_f32 v2, v58, v59
	v_cvt_pk_bf16_f32 v3, v60, v61
	ds_read_b64_tr_b16 v[52:53], v14 offset:31744
	ds_read_b64_tr_b16 v[54:55], v14 offset:32256
	v_add_f32_e32 v4, v64, v15
	v_add_f32_e32 v51, v65, v4
	v_cvt_pk_bf16_f32 v4, v62, v63
	v_cvt_pk_bf16_f32 v5, v64, v65
	v_mfma_f32_32x32x16_bf16 v[98:113], v[158:161], v[130:133], v[98:113]
	s_add_i32 s1, s10, s70
	s_mov_b32 s2, m0
	s_mov_b32 m0, s1
	s_nop 0
	global_load_lds_dwordx4 v[188:189], off
	s_mov_b32 m0, s2
	s_add_i32 s1, s92, s39
	s_mov_b32 s2, m0
	s_mov_b32 m0, s1
	s_nop 0
	global_load_lds_dwordx4 v[186:187], off
	s_mov_b32 m0, s2
	s_waitcnt lgkmcnt(0)
	v_max_f32_e32 v50, v82, v83
	v_max3_f32 v62, v84, v85, v99
	v_max3_f32 v50, v50, v98, v100
	v_max3_f32 v50, v50, v101, v86
	v_max3_f32 v62, v62, v88, v89
	v_max3_f32 v50, v50, v87, v102
	v_max3_f32 v62, v62, v104, v105
	v_max3_f32 v50, v50, v103, v90
	v_max3_f32 v62, v62, v92, v93
	v_max3_f32 v50, v50, v91, v106
	v_max3_f32 v62, v62, v108, v109
	v_max3_f32 v50, v50, v107, v94
	v_max3_f32 v62, v62, v96, v97
	v_max3_f32 v63, v50, v95, v110
	v_max3_f32 v62, v62, v112, v113
	v_add_f32_e32 v50, v192, v51
	v_max3_f32 v51, v63, v111, v62
	v_mov_b32_e32 v62, v51
	s_nop 1
	v_permlane32_swap_b32_e32 v51, v62
	v_max_f32_e32 v62, v62, v62
	v_max_f32_e32 v51, v51, v51
	v_max_f32_e32 v51, v51, v62
	v_cmp_lt_f32_e32 vcc, s71, v51
	s_cmp_lg_u64 vcc, 0
	s_cselect_b64 s[0:1], -1, 0
	s_cbranch_vccnz .LBB0_559
